# in-proj gelu epilogue: -2log2e folded into the polynomial constants (one multiply less per element)
# baseline (speedup 1.0000x reference)
; __device__ __forceinline__ unsigned pk2(float lo, float hi) { return pg8::cvt_pk_bf16(lo, hi); }
; __device__ __forceinline__ float gelu_tanh(float x) {
;     const float u = x * (0.7978845608028654f + 0.035677408136300125f * x * x);
;     return x * __builtin_amdgcn_rcpf(1.0f + __builtin_amdgcn_exp2f(-2.8853900817779268f * u));
;     __device__ __forceinline__ void operator()(const f32x4 (&acc)[2][2][4][2], const pg8::Unit& u, int wr, int wc, int fr, int fq) const {
;     ...
;         } else {
;             const bool isv = pn >= 5;
;             bf16* dst = isv ? VG : U;
;             const int cb = ((pn - (isv ? 5 : 3)) * 4 + wc) * 64;
; #pragma unroll
;             for (int ai = 0; ai < 2; ++ai)
; #pragma unroll
;                 for (int m = 0; m < 4; ++m) {
;                     const int row = pm * 256 + ai * 128 + wr * 64 + m * 16 + fr;
;                     float s1 = 0.f, s2 = 0.f;
; #pragma unroll
;                     for (int bj = 0; bj < 2; ++bj) {
;                         f32x4 y0 = acc[ai][bj][m][0], y1 = acc[ai][bj][m][1];
; #pragma unroll
;                         for (int j = 0; j < 4; ++j) { y0[j] = gelu_tanh(y0[j]); y1[j] = gelu_tanh(y1[j]); }
;                         s1 += (y0[0] + y0[1]) + (y0[2] + y0[3]) + (y1[0] + y1[1]) + (y1[2] + y1[3]);
;                         s2 += (y0[0] * y0[0] + y0[1] * y0[1]) + (y0[2] * y0[2] + y0[3] * y0[3]) + (y1[0] * y1[0] + y1[1] * y1[1]) + (y1[2] * y1[2] + y1[3] * y1[3]);
;                         u32x4 w; w.x = pk2(y0[0], y0[1]); w.y = pk2(y0[2], y0[3]); w.z = pk2(y1[0], y1[1]); w.w = pk2(y1[2], y1[3]);
;                         *(u32x4*)(dst + (size_t)row * 512 + cb + 32 * bj + 8 * fq) = w;
;                     }
;                     if (isv) {
;                         s1 = sum_fq(s1); s2 = sum_fq(s2);
;                         if (fq == 0) { float* sp = stats + (size_t)row * 16 + ((pn - 5) * 4 + wc) * 2; sp[0] = s1; sp[1] = s2; }
;                     }
;                 }
.LBB0_322:
	s_and_b64 vcc, exec, s[6:7]
	s_cbranch_vccz .LBB0_359
	s_mov_b64 s[6:7], -1
	s_cmp_lg_u32 s94, 2
	v_lshl_add_u32 v128, s72, 8, v217
	v_lshlrev_b32_e32 v160, 1, v170
	s_cbranch_scc0 .LBB0_357
	s_cmp_gt_u32 s94, 4
	s_cselect_b64 vcc, -1, 0
	s_and_b64 s[6:7], vcc, exec
	s_mov_b32 s5, 0x140fa000
	s_cselect_b32 s5, s5, 0x11efa000
	s_add_u32 s5, s28, s5
	s_addc_u32 s17, s29, 0
	s_and_b64 s[6:7], vcc, exec
	s_mov_b32 s6, 0xfffffb
	s_cselect_b32 s6, s6, 0xfffffd
	s_add_i32 s6, s6, s94
	s_lshl_b32 s6, s6, 8
	v_mul_f32_e32 v129, 0xbdd2d3e7, v124
	s_or_b32 s6, s6, s81
	v_fmaak_f32 v129, v124, v129, 0xc0135761
	s_ashr_i32 s7, s6, 31
	v_mul_f32_e32 v129, v124, v129
	s_lshl_b64 s[6:7], s[6:7], 1
	s_add_u32 s16, s5, s6
	v_exp_f32_e32 v134, v129
	s_addc_u32 s17, s17, s7
	v_ashrrev_i32_e32 v129, 31, v128
	v_lshl_add_u64 v[130:131], s[16:17], 0, v[160:161]
	v_lshlrev_b64 v[132:133], 10, v[128:129]
	v_lshl_add_u64 v[152:153], v[130:131], 0, v[132:133]
	v_mul_f32_e32 v133, 0xbdd2d3e7, v120
	v_add_f32_e32 v132, 1.0, v134
	v_fmaak_f32 v133, v120, v133, 0xc0135761
	v_mul_f32_e32 v134, 0xbdd2d3e7, v125
	v_mul_f32_e32 v133, v120, v133
	v_fmaak_f32 v134, v125, v134, 0xc0135761
	v_mul_f32_e32 v134, v125, v134
	v_exp_f32_e32 v133, v133
	v_exp_f32_e32 v134, v134
	v_rcp_f32_e32 v132, v132
	v_add_f32_e32 v133, 1.0, v133
	v_rcp_f32_e32 v135, v133
	v_add_f32_e32 v133, 1.0, v134
	v_rcp_f32_e32 v134, v133
	v_mul_f32_e32 v133, 0xbdd2d3e7, v121
	v_fmaak_f32 v133, v121, v133, 0xc0135761
	v_mul_f32_e32 v133, v121, v133
	v_exp_f32_e32 v136, v133
	v_mul_f32_e32 v133, v124, v132
	v_mul_f32_e32 v132, v120, v135
	v_mul_f32_e32 v137, 0xbdd2d3e7, v122
	v_add_f32_e32 v135, 1.0, v136
	v_mul_f32_e32 v136, 0xbdd2d3e7, v126
	v_mul_f32_e32 v138, 0xbdd2d3e7, v127
	v_fmaak_f32 v136, v126, v136, 0xc0135761
	v_fmaak_f32 v137, v122, v137, 0xc0135761
	v_fmaak_f32 v138, v127, v138, 0xc0135761
	v_mul_f32_e32 v139, 0xbdd2d3e7, v123
	v_mul_f32_e32 v136, v126, v136
	v_mul_f32_e32 v137, v122, v137
	v_mul_f32_e32 v138, v127, v138
	v_fmaak_f32 v139, v123, v139, 0xc0135761
	v_mul_f32_e32 v139, v123, v139
	v_exp_f32_e32 v136, v136
	v_exp_f32_e32 v137, v137
	v_exp_f32_e32 v138, v138
	v_exp_f32_e32 v139, v139
	v_add_f32_e32 v136, 1.0, v136
	v_add_f32_e32 v137, 1.0, v137
	v_add_f32_e32 v138, 1.0, v138
	v_rcp_f32_e32 v136, v136
	v_rcp_f32_e32 v137, v137
	v_rcp_f32_e32 v140, v138
	v_add_f32_e32 v138, 1.0, v139
	v_rcp_f32_e32 v135, v135
	v_rcp_f32_e32 v139, v138
	v_mul_f32_e32 v142, 0xbdd2d3e7, v116
	v_fmaak_f32 v142, v116, v142, 0xc0135761
	v_mul_f32_e32 v142, v116, v142
	v_mul_f32_e32 v134, v125, v134
	v_mul_f32_e32 v136, v126, v136
	v_mul_f32_e32 v138, v122, v137
	v_mul_f32_e32 v137, v127, v140
	v_cvt_pk_bf16_f32 v140, v133, v134
	v_cvt_pk_bf16_f32 v141, v136, v137
	v_mul_f32_e32 v135, v121, v135
	v_mul_f32_e32 v139, v123, v139
	v_exp_f32_e32 v144, v142
	v_cvt_pk_bf16_f32 v142, v132, v135
	v_cvt_pk_bf16_f32 v143, v138, v139
	global_store_dwordx4 v[152:153], v[140:143], off
	v_mul_f32_e32 v146, 0xbdd2d3e7, v119
	v_mul_f32_e32 v145, 0xbdd2d3e7, v110
	v_mul_f32_e32 v141, 0xbdd2d3e7, v108
	v_fmaak_f32 v141, v108, v141, 0xc0135761
	v_mul_f32_e32 v142, 0xbdd2d3e7, v117
	v_mul_f32_e32 v141, v108, v141
	v_fmaak_f32 v142, v117, v142, 0xc0135761
	v_mul_f32_e32 v142, v117, v142
	v_exp_f32_e32 v141, v141
	v_exp_f32_e32 v142, v142
	v_add_f32_e32 v140, 1.0, v144
	v_add_f32_e32 v141, 1.0, v141
	v_rcp_f32_e32 v143, v141
	v_add_f32_e32 v141, 1.0, v142
	v_rcp_f32_e32 v142, v141
	v_mul_f32_e32 v141, 0xbdd2d3e7, v109
	v_fmaak_f32 v141, v109, v141, 0xc0135761
	v_mul_f32_e32 v141, v109, v141
	v_rcp_f32_e32 v140, v140
	v_exp_f32_e32 v144, v141
	v_fmaak_f32 v146, v119, v146, 0xc0135761
	v_mul_f32_e32 v147, 0xbdd2d3e7, v111
	v_mul_f32_e32 v141, v116, v140
	v_mul_f32_e32 v140, v108, v143
	v_add_f32_e32 v143, 1.0, v144
	v_mul_f32_e32 v144, 0xbdd2d3e7, v118
	v_fmaak_f32 v144, v118, v144, 0xc0135761
	v_fmaak_f32 v145, v110, v145, 0xc0135761
	v_mul_f32_e32 v146, v119, v146
	v_fmaak_f32 v147, v111, v147, 0xc0135761
	v_mul_f32_e32 v144, v118, v144
	v_mul_f32_e32 v145, v110, v145
	v_mul_f32_e32 v147, v111, v147
	v_exp_f32_e32 v146, v146
	v_exp_f32_e32 v144, v144
	v_exp_f32_e32 v145, v145
	v_exp_f32_e32 v147, v147
	v_add_f32_e32 v146, 1.0, v146
	s_lshl_b32 s5, s94, 3
	v_add_f32_e32 v144, 1.0, v144
	v_add_f32_e32 v145, 1.0, v145
	v_rcp_f32_e32 v148, v146
	v_add_f32_e32 v146, 1.0, v147
	s_add_i32 s72, s25, s5
	v_rcp_f32_e32 v143, v143
	v_rcp_f32_e32 v144, v144
	v_rcp_f32_e32 v145, v145
	v_rcp_f32_e32 v147, v146
	s_lshl_b64 s[6:7], s[72:73], 2
	s_add_u32 s6, s40, s6
	s_addc_u32 s7, s41, s7
	s_cmp_lt_u32 s94, 5
	v_mul_f32_e32 v142, v117, v142
	v_mul_f32_e32 v143, v109, v143
	v_mul_f32_e32 v144, v118, v144
	v_mul_f32_e32 v146, v110, v145
	v_mul_f32_e32 v145, v119, v148
	v_mul_f32_e32 v147, v111, v147
	v_cvt_pk_bf16_f32 v148, v141, v142
	v_cvt_pk_bf16_f32 v149, v144, v145
	v_cvt_pk_bf16_f32 v150, v140, v143
	v_cvt_pk_bf16_f32 v151, v146, v147
	global_store_dwordx4 v[152:153], v[148:151], off offset:64
	s_cbranch_scc1 .LBB0_328
	s_nop 0
	v_mul_f32_e32 v149, v134, v134
	v_mul_f32_e32 v150, v137, v137
	v_fmac_f32_e32 v149, v133, v133
	v_fmac_f32_e32 v150, v136, v136
	v_add_f32_e32 v149, v149, v150
	v_mul_f32_e32 v150, v135, v135
	v_fmac_f32_e32 v150, v132, v132
	v_add_f32_e32 v133, v133, v134
	v_add_f32_e32 v134, v136, v137
	v_mul_f32_e32 v148, v139, v139
	v_add_f32_e32 v149, v149, v150
	v_mul_f32_e32 v150, v142, v142
	v_mul_f32_e32 v151, v145, v145
	v_add_f32_e32 v133, v133, v134
	v_add_f32_e32 v132, v132, v135
	v_add_f32_e32 v134, v141, v142
	v_add_f32_e32 v135, v144, v145
	v_fmac_f32_e32 v148, v138, v138
	v_fmac_f32_e32 v150, v141, v141
	v_fmac_f32_e32 v151, v144, v144
	v_add_f32_e32 v138, v138, v139
	v_add_f32_e32 v132, v133, v132
	v_add_f32_e32 v134, v134, v135
	v_add_f32_e32 v135, v140, v143
	v_add_f32_e32 v150, v150, v151
	v_mul_f32_e32 v151, v143, v143
	v_add_f32_e32 v132, v138, v132
	v_add_f32_e32 v133, v146, v147
	v_add_f32_e32 v134, v134, v135
	v_add_f32_e32 v148, v148, v149
	v_mul_f32_e32 v149, v147, v147
	v_fmac_f32_e32 v151, v140, v140
	v_add_f32_e32 v132, 0, v132
	v_add_f32_e32 v133, v133, v134
	v_fmac_f32_e32 v149, v146, v146
	v_add_f32_e32 v150, v150, v151
	v_add_f32_e32 v132, v132, v133
	v_add_f32_e32 v149, v149, v150
	v_mov_b32_e32 v133, v132
	v_add_f32_e32 v148, v148, v149
	s_nop 0
	v_permlane16_swap_b32_e32 v132, v133
	v_add_f32_e32 v132, v132, v133
	v_mov_b32_e32 v133, v148
	s_nop 1
	v_permlane16_swap_b32_e32 v148, v133
	v_add_f32_e32 v133, v148, v133
	v_mov_b32_e32 v134, v132
	v_mov_b32_e32 v135, v133
	s_nop 0
	v_permlane32_swap_b32_e32 v132, v134
	v_permlane32_swap_b32_e32 v133, v135
	s_and_saveexec_b64 s[16:17], s[12:13]
	s_cbranch_execz .LBB0_327
	v_lshlrev_b64 v[136:137], 6, v[128:129]
	v_lshl_add_u64 v[136:137], s[6:7], 0, v[136:137]
	v_pk_add_f32 v[132:133], v[132:133], v[134:135]
	global_store_dwordx2 v[136:137], v[132:133], off

; __device__ __forceinline__ unsigned pk2(float lo, float hi) { return pg8::cvt_pk_bf16(lo, hi); }
; __device__ __forceinline__ float gelu_tanh(float x) {
;     const float u = x * (0.7978845608028654f + 0.035677408136300125f * x * x);
;     return x * __builtin_amdgcn_rcpf(1.0f + __builtin_amdgcn_exp2f(-2.8853900817779268f * u));
;     __device__ __forceinline__ void operator()(const f32x4 (&acc)[2][2][4][2], const pg8::Unit& u, int wr, int wc, int fr, int fq) const {
;     ...
;         } else {
;             const bool isv = pn >= 5;
;             bf16* dst = isv ? VG : U;
;             const int cb = ((pn - (isv ? 5 : 3)) * 4 + wc) * 64;
; #pragma unroll
;             for (int ai = 0; ai < 2; ++ai)
; #pragma unroll
;                 for (int m = 0; m < 4; ++m) {
;                     const int row = pm * 256 + ai * 128 + wr * 64 + m * 16 + fr;
;                     float s1 = 0.f, s2 = 0.f;
; #pragma unroll
;                     for (int bj = 0; bj < 2; ++bj) {
;                         f32x4 y0 = acc[ai][bj][m][0], y1 = acc[ai][bj][m][1];
; #pragma unroll
;                         for (int j = 0; j < 4; ++j) { y0[j] = gelu_tanh(y0[j]); y1[j] = gelu_tanh(y1[j]); }
;                         s1 += (y0[0] + y0[1]) + (y0[2] + y0[3]) + (y1[0] + y1[1]) + (y1[2] + y1[3]);
;                         s2 += (y0[0] * y0[0] + y0[1] * y0[1]) + (y0[2] * y0[2] + y0[3] * y0[3]) + (y1[0] * y1[0] + y1[1] * y1[1]) + (y1[2] * y1[2] + y1[3] * y1[3]);
;                         u32x4 w; w.x = pk2(y0[0], y0[1]); w.y = pk2(y0[2], y0[3]); w.z = pk2(y1[0], y1[1]); w.w = pk2(y1[2], y1[3]);
;                         *(u32x4*)(dst + (size_t)row * 512 + cb + 32 * bj + 8 * fq) = w;
;                     }
;                     if (isv) {
;                         s1 = sum_fq(s1); s2 = sum_fq(s2);
;                         if (fq == 0) { float* sp = stats + (size_t)row * 16 + ((pn - 5) * 4 + wc) * 2; sp[0] = s1; sp[1] = s2; }
;                     }
;                 }
.LBB0_328:
	v_mul_f32_e32 v129, 0xbdd2d3e7, v112
	v_mul_f32_e32 v136, 0xbdd2d3e7, v104
	v_mul_f32_e32 v137, 0xbdd2d3e7, v113
	v_mul_f32_e32 v138, 0xbdd2d3e7, v105
	v_mul_f32_e32 v139, 0xbdd2d3e7, v114
	v_mul_f32_e32 v140, 0xbdd2d3e7, v106
	v_mul_f32_e32 v141, 0xbdd2d3e7, v115
	v_mul_f32_e32 v142, 0xbdd2d3e7, v107
	v_fmaak_f32 v129, v112, v129, 0xc0135761
	v_fmaak_f32 v136, v104, v136, 0xc0135761
	v_fmaak_f32 v137, v113, v137, 0xc0135761
	v_fmaak_f32 v138, v105, v138, 0xc0135761
	v_fmaak_f32 v139, v114, v139, 0xc0135761
	v_fmaak_f32 v140, v106, v140, 0xc0135761
	v_fmaak_f32 v141, v115, v141, 0xc0135761
	v_fmaak_f32 v142, v107, v142, 0xc0135761
	v_mul_f32_e32 v129, v112, v129
	v_mul_f32_e32 v136, v104, v136
	v_mul_f32_e32 v137, v113, v137
	v_mul_f32_e32 v138, v105, v138
	v_mul_f32_e32 v139, v114, v139
	v_mul_f32_e32 v140, v106, v140
	v_mul_f32_e32 v141, v115, v141
	v_mul_f32_e32 v142, v107, v142
	v_exp_f32_e32 v129, v129
	v_exp_f32_e32 v136, v136
	v_exp_f32_e32 v137, v137
	v_exp_f32_e32 v138, v138
	v_exp_f32_e32 v139, v139
	v_exp_f32_e32 v140, v140
	v_exp_f32_e32 v141, v141
	v_exp_f32_e32 v142, v142
	v_add_f32_e32 v129, 1.0, v129
	v_add_f32_e32 v136, 1.0, v136
	v_add_f32_e32 v137, 1.0, v137
	v_add_f32_e32 v138, 1.0, v138
	v_add_f32_e32 v139, 1.0, v139
	v_add_f32_e32 v140, 1.0, v140
	v_add_f32_e32 v141, 1.0, v141
	v_add_f32_e32 v142, 1.0, v142
	v_rcp_f32_e32 v129, v129
	v_rcp_f32_e32 v136, v136
	v_rcp_f32_e32 v137, v137
	v_rcp_f32_e32 v138, v138
	v_rcp_f32_e32 v139, v139
	v_rcp_f32_e32 v140, v140
	v_rcp_f32_e32 v141, v141
	v_rcp_f32_e32 v142, v142
	v_or_b32_e32 v132, 16, v128
	v_ashrrev_i32_e32 v133, 31, v132
	v_lshlrev_b64 v[134:135], 10, v[132:133]
	v_lshl_add_u64 v[134:135], v[130:131], 0, v[134:135]
	v_mul_f32_e32 v129, v112, v129
	v_mul_f32_e32 v136, v104, v136
	v_mul_f32_e32 v137, v113, v137
	v_mul_f32_e32 v138, v105, v138
	v_mul_f32_e32 v139, v114, v139
	v_mul_f32_e32 v140, v106, v140
	v_mul_f32_e32 v141, v115, v141
	v_mul_f32_e32 v142, v107, v142
	v_cvt_pk_bf16_f32 v144, v129, v137
	v_cvt_pk_bf16_f32 v145, v139, v141
	v_cvt_pk_bf16_f32 v146, v136, v138
	v_cvt_pk_bf16_f32 v147, v140, v142
	global_store_dwordx4 v[134:135], v[144:147], off
	v_mul_f32_e32 v143, 0xbdd2d3e7, v100
	v_mul_f32_e32 v148, 0xbdd2d3e7, v94
	v_mul_f32_e32 v144, 0xbdd2d3e7, v92
	v_mul_f32_e32 v145, 0xbdd2d3e7, v101
	v_mul_f32_e32 v146, 0xbdd2d3e7, v93
	v_mul_f32_e32 v147, 0xbdd2d3e7, v102
	v_mul_f32_e32 v149, 0xbdd2d3e7, v103
	v_mul_f32_e32 v150, 0xbdd2d3e7, v95
	v_fmaak_f32 v143, v100, v143, 0xc0135761
	v_fmaak_f32 v144, v92, v144, 0xc0135761
	v_fmaak_f32 v145, v101, v145, 0xc0135761
	v_fmaak_f32 v146, v93, v146, 0xc0135761
	v_fmaak_f32 v147, v102, v147, 0xc0135761
	v_fmaak_f32 v148, v94, v148, 0xc0135761
	v_fmaak_f32 v149, v103, v149, 0xc0135761
	v_fmaak_f32 v150, v95, v150, 0xc0135761
	v_mul_f32_e32 v143, v100, v143
	v_mul_f32_e32 v144, v92, v144
	v_mul_f32_e32 v145, v101, v145
	v_mul_f32_e32 v146, v93, v146
	v_mul_f32_e32 v147, v102, v147
	v_mul_f32_e32 v148, v94, v148
	v_mul_f32_e32 v149, v103, v149
	v_mul_f32_e32 v150, v95, v150
	v_exp_f32_e32 v143, v143
	v_exp_f32_e32 v144, v144
	v_exp_f32_e32 v145, v145
	v_exp_f32_e32 v146, v146
	v_exp_f32_e32 v147, v147
	v_exp_f32_e32 v148, v148
	v_exp_f32_e32 v149, v149
	v_exp_f32_e32 v150, v150
	v_add_f32_e32 v143, 1.0, v143
	v_add_f32_e32 v144, 1.0, v144
	v_add_f32_e32 v145, 1.0, v145
	v_add_f32_e32 v146, 1.0, v146
	v_add_f32_e32 v147, 1.0, v147
	v_add_f32_e32 v148, 1.0, v148
	v_add_f32_e32 v149, 1.0, v149
	v_add_f32_e32 v150, 1.0, v150
	v_rcp_f32_e32 v143, v143
	v_rcp_f32_e32 v144, v144
	v_rcp_f32_e32 v145, v145
	v_rcp_f32_e32 v146, v146
	v_rcp_f32_e32 v147, v147
	v_rcp_f32_e32 v148, v148
	v_rcp_f32_e32 v149, v149
	v_rcp_f32_e32 v150, v150
	v_mul_f32_e32 v143, v100, v143
	v_mul_f32_e32 v144, v92, v144
	v_mul_f32_e32 v145, v101, v145
	v_mul_f32_e32 v146, v93, v146
	v_mul_f32_e32 v147, v102, v147
	v_mul_f32_e32 v148, v94, v148
	v_mul_f32_e32 v149, v103, v149
	v_mul_f32_e32 v150, v95, v150
	v_cvt_pk_bf16_f32 v152, v143, v145
	v_cvt_pk_bf16_f32 v153, v147, v149
	v_cvt_pk_bf16_f32 v154, v144, v146
	v_cvt_pk_bf16_f32 v155, v148, v150
	global_store_dwordx4 v[134:135], v[152:155], off offset:64
	v_cndmask_b32_e64 v134, 0, 1, vcc
	v_cmp_ne_u32_e64 s[16:17], 1, v134
	s_andn2_b64 vcc, exec, vcc
	s_cbranch_vccnz .LBB0_332
	v_mul_f32_e32 v135, v137, v137
	v_mul_f32_e32 v151, v141, v141
	v_fmac_f32_e32 v135, v129, v129
	v_fmac_f32_e32 v151, v139, v139
	v_add_f32_e32 v135, v135, v151
	v_mul_f32_e32 v151, v138, v138
	v_fmac_f32_e32 v151, v136, v136
	v_add_f32_e32 v135, v135, v151
	v_mul_f32_e32 v151, v145, v145
	v_mul_f32_e32 v152, v149, v149
	v_mul_f32_e32 v134, v142, v142
	v_fmac_f32_e32 v151, v143, v143
	v_fmac_f32_e32 v152, v147, v147
	v_fmac_f32_e32 v134, v140, v140
	v_add_f32_e32 v151, v151, v152
	v_mul_f32_e32 v152, v146, v146
	v_add_f32_e32 v134, v134, v135
	v_mul_f32_e32 v135, v150, v150
	v_fmac_f32_e32 v152, v144, v144
	v_add_f32_e32 v129, v129, v137
	v_add_f32_e32 v137, v139, v141
	v_fmac_f32_e32 v135, v148, v148
	v_add_f32_e32 v151, v151, v152
	v_add_f32_e32 v129, v129, v137
	v_add_f32_e32 v136, v136, v138
	v_add_f32_e32 v135, v135, v151
	v_add_f32_e32 v129, v129, v136
	v_add_f32_e32 v136, v143, v145
	v_add_f32_e32 v137, v147, v149
	v_add_f32_e32 v135, v134, v135
	v_add_f32_e32 v134, v140, v142
	v_add_f32_e32 v136, v136, v137
	v_add_f32_e32 v137, v144, v146
	v_add_f32_e32 v129, v134, v129
	v_add_f32_e32 v134, v148, v150
	v_add_f32_e32 v136, v136, v137
	v_add_f32_e32 v129, 0, v129
	v_add_f32_e32 v134, v134, v136
	v_add_f32_e32 v129, v129, v134
	v_mov_b32_e32 v134, v129
	s_nop 1
	v_permlane16_swap_b32_e32 v129, v134
	v_add_f32_e32 v134, v129, v134
	v_mov_b32_e32 v129, v135
	s_nop 1
	v_permlane16_swap_b32_e32 v135, v129
	v_add_f32_e32 v135, v135, v129
	v_mov_b32_e32 v136, v134
	v_mov_b32_e32 v137, v135
	s_nop 0
	v_permlane32_swap_b32_e32 v134, v136
	v_permlane32_swap_b32_e32 v135, v137
	s_and_saveexec_b64 s[26:27], s[12:13]
	s_cbranch_execz .LBB0_331
	v_lshlrev_b64 v[132:133], 6, v[132:133]
	v_lshl_add_u64 v[132:133], s[6:7], 0, v[132:133]
	v_pk_add_f32 v[134:135], v[134:135], v[136:137]
	global_store_dwordx2 v[132:133], v[134:135], off

; __device__ __forceinline__ unsigned pk2(float lo, float hi) { return pg8::cvt_pk_bf16(lo, hi); }
; __device__ __forceinline__ float gelu_tanh(float x) {
;     const float u = x * (0.7978845608028654f + 0.035677408136300125f * x * x);
;     return x * __builtin_amdgcn_rcpf(1.0f + __builtin_amdgcn_exp2f(-2.8853900817779268f * u));
;     __device__ __forceinline__ void operator()(const f32x4 (&acc)[2][2][4][2], const pg8::Unit& u, int wr, int wc, int fr, int fq) const {
;     ...
;         } else {
;             const bool isv = pn >= 5;
;             bf16* dst = isv ? VG : U;
;             const int cb = ((pn - (isv ? 5 : 3)) * 4 + wc) * 64;
; #pragma unroll
;             for (int ai = 0; ai < 2; ++ai)
; #pragma unroll
;                 for (int m = 0; m < 4; ++m) {
;                     const int row = pm * 256 + ai * 128 + wr * 64 + m * 16 + fr;
;                     float s1 = 0.f, s2 = 0.f;
; #pragma unroll
;                     for (int bj = 0; bj < 2; ++bj) {
;                         f32x4 y0 = acc[ai][bj][m][0], y1 = acc[ai][bj][m][1];
; #pragma unroll
;                         for (int j = 0; j < 4; ++j) { y0[j] = gelu_tanh(y0[j]); y1[j] = gelu_tanh(y1[j]); }
;                         s1 += (y0[0] + y0[1]) + (y0[2] + y0[3]) + (y1[0] + y1[1]) + (y1[2] + y1[3]);
;                         s2 += (y0[0] * y0[0] + y0[1] * y0[1]) + (y0[2] * y0[2] + y0[3] * y0[3]) + (y1[0] * y1[0] + y1[1] * y1[1]) + (y1[2] * y1[2] + y1[3] * y1[3]);
;                         u32x4 w; w.x = pk2(y0[0], y0[1]); w.y = pk2(y0[2], y0[3]); w.z = pk2(y1[0], y1[1]); w.w = pk2(y1[2], y1[3]);
;                         *(u32x4*)(dst + (size_t)row * 512 + cb + 32 * bj + 8 * fq) = w;
;                     }
;                     if (isv) {
;                         s1 = sum_fq(s1); s2 = sum_fq(s2);
;                         if (fq == 0) { float* sp = stats + (size_t)row * 16 + ((pn - 5) * 4 + wc) * 2; sp[0] = s1; sp[1] = s2; }
;                     }
;                 }
.LBB0_332:
	v_or_b32_e32 v132, 32, v128
	v_ashrrev_i32_e32 v133, 31, v132
	v_lshlrev_b64 v[134:135], 10, v[132:133]
	v_lshl_add_u64 v[154:155], v[130:131], 0, v[134:135]
	v_mul_f32_e32 v134, 0xbdd2d3e7, v88
	v_fmaak_f32 v134, v88, v134, 0xc0135761
	v_mul_f32_e32 v135, 0xbdd2d3e7, v97
	v_mul_f32_e32 v134, v88, v134
	v_fmaak_f32 v135, v97, v135, 0xc0135761
	v_mul_f32_e32 v135, v97, v135
	v_exp_f32_e32 v134, v134
	v_mul_f32_e32 v129, 0xbdd2d3e7, v96
	v_exp_f32_e32 v135, v135
	v_fmaak_f32 v129, v96, v129, 0xc0135761
	v_mul_f32_e32 v129, v96, v129
	v_add_f32_e32 v134, 1.0, v134
	v_exp_f32_e32 v129, v129
	v_rcp_f32_e32 v136, v134
	v_add_f32_e32 v134, 1.0, v135
	v_rcp_f32_e32 v135, v134
	v_mul_f32_e32 v134, 0xbdd2d3e7, v89
	v_fmaak_f32 v134, v89, v134, 0xc0135761
	v_mul_f32_e32 v134, v89, v134
	v_add_f32_e32 v129, 1.0, v129
	v_rcp_f32_e32 v129, v129
	v_exp_f32_e32 v137, v134
	v_mul_f32_e32 v139, 0xbdd2d3e7, v99
	v_mul_f32_e32 v138, 0xbdd2d3e7, v90
	v_mul_f32_e32 v134, v96, v129
	v_mul_f32_e32 v129, v88, v136
	v_add_f32_e32 v136, 1.0, v137
	v_mul_f32_e32 v137, 0xbdd2d3e7, v98
	v_fmaak_f32 v139, v99, v139, 0xc0135761
	v_mul_f32_e32 v140, 0xbdd2d3e7, v91
	v_fmaak_f32 v137, v98, v137, 0xc0135761
	v_fmaak_f32 v138, v90, v138, 0xc0135761
	v_mul_f32_e32 v139, v99, v139
	v_fmaak_f32 v140, v91, v140, 0xc0135761
	v_mul_f32_e32 v137, v98, v137
	v_mul_f32_e32 v138, v90, v138
	v_mul_f32_e32 v140, v91, v140
	v_exp_f32_e32 v139, v139
	v_exp_f32_e32 v137, v137
	v_exp_f32_e32 v138, v138
	v_exp_f32_e32 v140, v140
	v_add_f32_e32 v139, 1.0, v139
	v_add_f32_e32 v137, 1.0, v137
	v_add_f32_e32 v138, 1.0, v138
	v_rcp_f32_e32 v141, v139
	v_add_f32_e32 v139, 1.0, v140
	v_rcp_f32_e32 v136, v136
	v_rcp_f32_e32 v137, v137
	v_rcp_f32_e32 v138, v138
	v_rcp_f32_e32 v140, v139
	v_mul_f32_e32 v135, v97, v135
	v_cvt_pk_bf16_f32 v142, v134, v135
	v_mul_f32_e32 v136, v89, v136
	v_mul_f32_e32 v137, v98, v137
	v_mul_f32_e32 v139, v90, v138
	v_mul_f32_e32 v138, v99, v141
	v_mul_f32_e32 v140, v91, v140
	v_cvt_pk_bf16_f32 v143, v137, v138
	v_cvt_pk_bf16_f32 v144, v129, v136
	v_cvt_pk_bf16_f32 v145, v139, v140
	global_store_dwordx4 v[154:155], v[142:145], off
	v_mul_f32_e32 v141, 0xbdd2d3e7, v84
	v_fmaak_f32 v141, v84, v141, 0xc0135761
	v_mul_f32_e32 v142, 0xbdd2d3e7, v76
	v_fmaak_f32 v142, v76, v142, 0xc0135761
	v_mul_f32_e32 v143, 0xbdd2d3e7, v85
	v_mul_f32_e32 v142, v76, v142
	v_fmaak_f32 v143, v85, v143, 0xc0135761
	v_mul_f32_e32 v143, v85, v143
	v_exp_f32_e32 v142, v142
	v_exp_f32_e32 v143, v143
	v_mul_f32_e32 v141, v84, v141
	v_add_f32_e32 v142, 1.0, v142
	v_exp_f32_e32 v141, v141
	v_rcp_f32_e32 v144, v142
	v_add_f32_e32 v142, 1.0, v143
	v_rcp_f32_e32 v143, v142
	v_mul_f32_e32 v142, 0xbdd2d3e7, v77
	v_fmaak_f32 v142, v77, v142, 0xc0135761
	v_mul_f32_e32 v142, v77, v142
	v_add_f32_e32 v141, 1.0, v141
	v_rcp_f32_e32 v141, v141
	v_exp_f32_e32 v145, v142
	v_mul_f32_e32 v147, 0xbdd2d3e7, v87
	v_mul_f32_e32 v146, 0xbdd2d3e7, v78
	v_mul_f32_e32 v142, v84, v141
	v_mul_f32_e32 v141, v76, v144
	v_add_f32_e32 v144, 1.0, v145
	v_mul_f32_e32 v145, 0xbdd2d3e7, v86
	v_fmaak_f32 v147, v87, v147, 0xc0135761
	v_mul_f32_e32 v148, 0xbdd2d3e7, v79
	v_fmaak_f32 v145, v86, v145, 0xc0135761
	v_fmaak_f32 v146, v78, v146, 0xc0135761
	v_mul_f32_e32 v147, v87, v147
	v_fmaak_f32 v148, v79, v148, 0xc0135761
	v_mul_f32_e32 v145, v86, v145
	v_mul_f32_e32 v146, v78, v146
	v_mul_f32_e32 v148, v79, v148
	v_exp_f32_e32 v147, v147
	v_exp_f32_e32 v145, v145
	v_exp_f32_e32 v146, v146
	v_exp_f32_e32 v148, v148
	v_add_f32_e32 v147, 1.0, v147
	v_add_f32_e32 v145, 1.0, v145
	v_add_f32_e32 v146, 1.0, v146
	v_rcp_f32_e32 v149, v147
	v_add_f32_e32 v147, 1.0, v148
	v_rcp_f32_e32 v144, v144
	v_rcp_f32_e32 v145, v145
	v_rcp_f32_e32 v146, v146
	v_rcp_f32_e32 v148, v147
	v_mul_f32_e32 v143, v85, v143
	v_mul_f32_e32 v144, v77, v144
	v_mul_f32_e32 v145, v86, v145
	v_mul_f32_e32 v147, v78, v146
	v_mul_f32_e32 v146, v87, v149
	v_mul_f32_e32 v148, v79, v148
	s_and_b64 vcc, exec, s[16:17]
	v_cvt_pk_bf16_f32 v150, v142, v143
	v_cvt_pk_bf16_f32 v151, v145, v146
	v_cvt_pk_bf16_f32 v152, v141, v144
	v_cvt_pk_bf16_f32 v153, v147, v148
	global_store_dwordx4 v[154:155], v[150:153], off offset:64
	s_cbranch_vccnz .LBB0_336
	s_nop 0
	v_mul_f32_e32 v150, v135, v135
	v_mul_f32_e32 v151, v138, v138
	v_fmac_f32_e32 v150, v134, v134
	v_fmac_f32_e32 v151, v137, v137
	v_add_f32_e32 v150, v150, v151
	v_mul_f32_e32 v151, v136, v136
	v_fmac_f32_e32 v151, v129, v129
	v_add_f32_e32 v134, v134, v135
	v_add_f32_e32 v135, v137, v138
	v_mul_f32_e32 v149, v140, v140
	v_add_f32_e32 v150, v150, v151
	v_mul_f32_e32 v151, v143, v143
	v_mul_f32_e32 v152, v146, v146
	v_add_f32_e32 v134, v134, v135
	v_add_f32_e32 v129, v129, v136
	v_add_f32_e32 v135, v142, v143
	v_add_f32_e32 v136, v145, v146
	v_fmac_f32_e32 v149, v139, v139
	v_fmac_f32_e32 v151, v142, v142
	v_fmac_f32_e32 v152, v145, v145
	v_add_f32_e32 v139, v139, v140
	v_add_f32_e32 v129, v134, v129
	v_add_f32_e32 v135, v135, v136
	v_add_f32_e32 v136, v141, v144
	v_add_f32_e32 v151, v151, v152
	v_mul_f32_e32 v152, v144, v144
	v_add_f32_e32 v129, v139, v129
	v_add_f32_e32 v134, v147, v148
	v_add_f32_e32 v135, v135, v136
	v_add_f32_e32 v149, v149, v150
	v_mul_f32_e32 v150, v148, v148
	v_fmac_f32_e32 v152, v141, v141
	v_add_f32_e32 v129, 0, v129
	v_add_f32_e32 v134, v134, v135
	v_fmac_f32_e32 v150, v147, v147
	v_add_f32_e32 v151, v151, v152
	v_add_f32_e32 v129, v129, v134
	v_add_f32_e32 v150, v150, v151
	v_mov_b32_e32 v134, v129
	v_add_f32_e32 v149, v149, v150
	s_nop 0
	v_permlane16_swap_b32_e32 v129, v134
	v_add_f32_e32 v134, v129, v134
	v_mov_b32_e32 v129, v149
	s_nop 1
	v_permlane16_swap_b32_e32 v149, v129
	v_add_f32_e32 v135, v149, v129
	v_mov_b32_e32 v136, v134
	v_mov_b32_e32 v137, v135
	s_nop 0
	v_permlane32_swap_b32_e32 v134, v136
	v_permlane32_swap_b32_e32 v135, v137
	s_and_saveexec_b64 s[26:27], s[12:13]
	s_cbranch_execz .LBB0_335
	v_lshlrev_b64 v[132:133], 6, v[132:133]
	v_lshl_add_u64 v[132:133], s[6:7], 0, v[132:133]
	v_pk_add_f32 v[134:135], v[134:135], v[136:137]
	global_store_dwordx2 v[132:133], v[134:135], off

; __device__ __forceinline__ unsigned pk2(float lo, float hi) { return pg8::cvt_pk_bf16(lo, hi); }
; __device__ __forceinline__ float gelu_tanh(float x) {
;     const float u = x * (0.7978845608028654f + 0.035677408136300125f * x * x);
;     return x * __builtin_amdgcn_rcpf(1.0f + __builtin_amdgcn_exp2f(-2.8853900817779268f * u));
;     __device__ __forceinline__ void operator()(const f32x4 (&acc)[2][2][4][2], const pg8::Unit& u, int wr, int wc, int fr, int fq) const {
;     ...
;         } else {
;             const bool isv = pn >= 5;
;             bf16* dst = isv ? VG : U;
;             const int cb = ((pn - (isv ? 5 : 3)) * 4 + wc) * 64;
; #pragma unroll
;             for (int ai = 0; ai < 2; ++ai)
; #pragma unroll
;                 for (int m = 0; m < 4; ++m) {
;                     const int row = pm * 256 + ai * 128 + wr * 64 + m * 16 + fr;
;                     float s1 = 0.f, s2 = 0.f;
; #pragma unroll
;                     for (int bj = 0; bj < 2; ++bj) {
;                         f32x4 y0 = acc[ai][bj][m][0], y1 = acc[ai][bj][m][1];
; #pragma unroll
;                         for (int j = 0; j < 4; ++j) { y0[j] = gelu_tanh(y0[j]); y1[j] = gelu_tanh(y1[j]); }
;                         s1 += (y0[0] + y0[1]) + (y0[2] + y0[3]) + (y1[0] + y1[1]) + (y1[2] + y1[3]);
;                         s2 += (y0[0] * y0[0] + y0[1] * y0[1]) + (y0[2] * y0[2] + y0[3] * y0[3]) + (y1[0] * y1[0] + y1[1] * y1[1]) + (y1[2] * y1[2] + y1[3] * y1[3]);
;                         u32x4 w; w.x = pk2(y0[0], y0[1]); w.y = pk2(y0[2], y0[3]); w.z = pk2(y1[0], y1[1]); w.w = pk2(y1[2], y1[3]);
;                         *(u32x4*)(dst + (size_t)row * 512 + cb + 32 * bj + 8 * fq) = w;
;                     }
;                     if (isv) {
;                         s1 = sum_fq(s1); s2 = sum_fq(s2);
;                         if (fq == 0) { float* sp = stats + (size_t)row * 16 + ((pn - 5) * 4 + wc) * 2; sp[0] = s1; sp[1] = s2; }
;                     }
;                 }
.LBB0_336:
	v_or_b32_e32 v132, 48, v128
	v_ashrrev_i32_e32 v133, 31, v132
	v_lshlrev_b64 v[134:135], 10, v[132:133]
	v_lshl_add_u64 v[154:155], v[130:131], 0, v[134:135]
	v_mul_f32_e32 v134, 0xbdd2d3e7, v72
	v_fmaak_f32 v134, v72, v134, 0xc0135761
	v_mul_f32_e32 v135, 0xbdd2d3e7, v81
	v_mul_f32_e32 v134, v72, v134
	v_fmaak_f32 v135, v81, v135, 0xc0135761
	v_mul_f32_e32 v135, v81, v135
	v_exp_f32_e32 v134, v134
	v_mul_f32_e32 v129, 0xbdd2d3e7, v80
	v_exp_f32_e32 v135, v135
	v_fmaak_f32 v129, v80, v129, 0xc0135761
	v_mul_f32_e32 v129, v80, v129
	v_add_f32_e32 v134, 1.0, v134
	v_exp_f32_e32 v129, v129
	v_rcp_f32_e32 v136, v134
	v_add_f32_e32 v134, 1.0, v135
	v_rcp_f32_e32 v135, v134
	v_mul_f32_e32 v134, 0xbdd2d3e7, v73
	v_fmaak_f32 v134, v73, v134, 0xc0135761
	v_mul_f32_e32 v134, v73, v134
	v_add_f32_e32 v129, 1.0, v129
	v_rcp_f32_e32 v129, v129
	v_exp_f32_e32 v137, v134
	v_mul_f32_e32 v139, 0xbdd2d3e7, v83
	v_mul_f32_e32 v138, 0xbdd2d3e7, v74
	v_mul_f32_e32 v134, v80, v129
	v_mul_f32_e32 v129, v72, v136
	v_add_f32_e32 v136, 1.0, v137
	v_mul_f32_e32 v137, 0xbdd2d3e7, v82
	v_fmaak_f32 v139, v83, v139, 0xc0135761
	v_mul_f32_e32 v140, 0xbdd2d3e7, v75
	v_fmaak_f32 v137, v82, v137, 0xc0135761
	v_fmaak_f32 v138, v74, v138, 0xc0135761
	v_mul_f32_e32 v139, v83, v139
	v_fmaak_f32 v140, v75, v140, 0xc0135761
	v_mul_f32_e32 v137, v82, v137
	v_mul_f32_e32 v138, v74, v138
	v_mul_f32_e32 v140, v75, v140
	v_exp_f32_e32 v139, v139
	v_exp_f32_e32 v137, v137
	v_exp_f32_e32 v138, v138
	v_exp_f32_e32 v140, v140
	v_add_f32_e32 v139, 1.0, v139
	v_add_f32_e32 v137, 1.0, v137
	v_add_f32_e32 v138, 1.0, v138
	v_rcp_f32_e32 v141, v139
	v_add_f32_e32 v139, 1.0, v140
	v_rcp_f32_e32 v136, v136
	v_rcp_f32_e32 v137, v137
	v_rcp_f32_e32 v138, v138
	v_rcp_f32_e32 v140, v139
	v_mul_f32_e32 v135, v81, v135
	v_cvt_pk_bf16_f32 v142, v134, v135
	v_mul_f32_e32 v136, v73, v136
	v_mul_f32_e32 v137, v82, v137
	v_mul_f32_e32 v139, v74, v138
	v_mul_f32_e32 v138, v83, v141
	v_mul_f32_e32 v140, v75, v140
	v_cvt_pk_bf16_f32 v143, v137, v138
	v_cvt_pk_bf16_f32 v144, v129, v136
	v_cvt_pk_bf16_f32 v145, v139, v140
	global_store_dwordx4 v[154:155], v[142:145], off
	v_mul_f32_e32 v141, 0xbdd2d3e7, v68
	v_fmaak_f32 v141, v68, v141, 0xc0135761
	v_mul_f32_e32 v142, 0xbdd2d3e7, v64
	v_fmaak_f32 v142, v64, v142, 0xc0135761
	v_mul_f32_e32 v143, 0xbdd2d3e7, v69
	v_mul_f32_e32 v142, v64, v142
	v_fmaak_f32 v143, v69, v143, 0xc0135761
	v_mul_f32_e32 v143, v69, v143
	v_exp_f32_e32 v142, v142
	v_exp_f32_e32 v143, v143
	v_mul_f32_e32 v141, v68, v141
	v_add_f32_e32 v142, 1.0, v142
	v_exp_f32_e32 v141, v141
	v_rcp_f32_e32 v144, v142
	v_add_f32_e32 v142, 1.0, v143
	v_rcp_f32_e32 v143, v142
	v_mul_f32_e32 v142, 0xbdd2d3e7, v65
	v_fmaak_f32 v142, v65, v142, 0xc0135761
	v_mul_f32_e32 v142, v65, v142
	v_add_f32_e32 v141, 1.0, v141
	v_rcp_f32_e32 v141, v141
	v_exp_f32_e32 v145, v142
	v_mul_f32_e32 v147, 0xbdd2d3e7, v71
	v_mul_f32_e32 v146, 0xbdd2d3e7, v66
	v_mul_f32_e32 v142, v68, v141
	v_mul_f32_e32 v141, v64, v144
	v_add_f32_e32 v144, 1.0, v145
	v_mul_f32_e32 v145, 0xbdd2d3e7, v70
	v_fmaak_f32 v147, v71, v147, 0xc0135761
	v_mul_f32_e32 v148, 0xbdd2d3e7, v67
	v_fmaak_f32 v145, v70, v145, 0xc0135761
	v_fmaak_f32 v146, v66, v146, 0xc0135761
	v_mul_f32_e32 v147, v71, v147
	v_fmaak_f32 v148, v67, v148, 0xc0135761
	v_mul_f32_e32 v145, v70, v145
	v_mul_f32_e32 v146, v66, v146
	v_mul_f32_e32 v148, v67, v148
	v_exp_f32_e32 v147, v147
	v_exp_f32_e32 v145, v145
	v_exp_f32_e32 v146, v146
	v_exp_f32_e32 v148, v148
	v_add_f32_e32 v147, 1.0, v147
	v_add_f32_e32 v145, 1.0, v145
	v_add_f32_e32 v146, 1.0, v146
	v_rcp_f32_e32 v149, v147
	v_add_f32_e32 v147, 1.0, v148
	v_rcp_f32_e32 v144, v144
	v_rcp_f32_e32 v145, v145
	v_rcp_f32_e32 v146, v146
	v_rcp_f32_e32 v148, v147
	v_mul_f32_e32 v143, v69, v143
	v_mul_f32_e32 v144, v65, v144
	v_mul_f32_e32 v145, v70, v145
	v_mul_f32_e32 v147, v66, v146
	v_mul_f32_e32 v146, v71, v149
	v_mul_f32_e32 v148, v67, v148
	s_and_b64 vcc, exec, s[16:17]
	v_cvt_pk_bf16_f32 v150, v142, v143
	v_cvt_pk_bf16_f32 v151, v145, v146
	v_cvt_pk_bf16_f32 v152, v141, v144
	v_cvt_pk_bf16_f32 v153, v147, v148
	global_store_dwordx4 v[154:155], v[150:153], off offset:64
	s_cbranch_vccnz .LBB0_340
	s_nop 0
	v_mul_f32_e32 v150, v135, v135
	v_mul_f32_e32 v151, v138, v138
	v_fmac_f32_e32 v150, v134, v134
	v_fmac_f32_e32 v151, v137, v137
	v_add_f32_e32 v150, v150, v151
	v_mul_f32_e32 v151, v136, v136
	v_fmac_f32_e32 v151, v129, v129
	v_add_f32_e32 v134, v134, v135
	v_add_f32_e32 v135, v137, v138
	v_mul_f32_e32 v149, v140, v140
	v_add_f32_e32 v150, v150, v151
	v_mul_f32_e32 v151, v143, v143
	v_mul_f32_e32 v152, v146, v146
	v_add_f32_e32 v134, v134, v135
	v_add_f32_e32 v129, v129, v136
	v_add_f32_e32 v135, v142, v143
	v_add_f32_e32 v136, v145, v146
	v_fmac_f32_e32 v149, v139, v139
	v_fmac_f32_e32 v151, v142, v142
	v_fmac_f32_e32 v152, v145, v145
	v_add_f32_e32 v139, v139, v140
	v_add_f32_e32 v129, v134, v129
	v_add_f32_e32 v135, v135, v136
	v_add_f32_e32 v136, v141, v144
	v_add_f32_e32 v151, v151, v152
	v_mul_f32_e32 v152, v144, v144
	v_add_f32_e32 v129, v139, v129
	v_add_f32_e32 v134, v147, v148
	v_add_f32_e32 v135, v135, v136
	v_add_f32_e32 v149, v149, v150
	v_mul_f32_e32 v150, v148, v148
	v_fmac_f32_e32 v152, v141, v141
	v_add_f32_e32 v129, 0, v129
	v_add_f32_e32 v134, v134, v135
	v_fmac_f32_e32 v150, v147, v147
	v_add_f32_e32 v151, v151, v152
	v_add_f32_e32 v129, v129, v134
	v_add_f32_e32 v150, v150, v151
	v_mov_b32_e32 v134, v129
	v_add_f32_e32 v149, v149, v150
	s_nop 0
	v_permlane16_swap_b32_e32 v129, v134
	v_add_f32_e32 v134, v129, v134
	v_mov_b32_e32 v129, v149
	s_nop 1
	v_permlane16_swap_b32_e32 v149, v129
	v_add_f32_e32 v135, v149, v129
	v_mov_b32_e32 v136, v134
	v_mov_b32_e32 v137, v135
	s_nop 0
	v_permlane32_swap_b32_e32 v134, v136
	v_permlane32_swap_b32_e32 v135, v137
	s_and_saveexec_b64 s[26:27], s[12:13]
	s_cbranch_execz .LBB0_339
	v_lshlrev_b64 v[132:133], 6, v[132:133]
	v_lshl_add_u64 v[132:133], s[6:7], 0, v[132:133]
	v_pk_add_f32 v[134:135], v[134:135], v[136:137]
	global_store_dwordx2 v[132:133], v[134:135], off

; __device__ __forceinline__ unsigned pk2(float lo, float hi) { return pg8::cvt_pk_bf16(lo, hi); }
; __device__ __forceinline__ float gelu_tanh(float x) {
;     const float u = x * (0.7978845608028654f + 0.035677408136300125f * x * x);
;     return x * __builtin_amdgcn_rcpf(1.0f + __builtin_amdgcn_exp2f(-2.8853900817779268f * u));
;     __device__ __forceinline__ void operator()(const f32x4 (&acc)[2][2][4][2], const pg8::Unit& u, int wr, int wc, int fr, int fq) const {
;     ...
;         } else {
;             const bool isv = pn >= 5;
;             bf16* dst = isv ? VG : U;
;             const int cb = ((pn - (isv ? 5 : 3)) * 4 + wc) * 64;
; #pragma unroll
;             for (int ai = 0; ai < 2; ++ai)
; #pragma unroll
;                 for (int m = 0; m < 4; ++m) {
;                     const int row = pm * 256 + ai * 128 + wr * 64 + m * 16 + fr;
;                     float s1 = 0.f, s2 = 0.f;
; #pragma unroll
;                     for (int bj = 0; bj < 2; ++bj) {
;                         f32x4 y0 = acc[ai][bj][m][0], y1 = acc[ai][bj][m][1];
; #pragma unroll
;                         for (int j = 0; j < 4; ++j) { y0[j] = gelu_tanh(y0[j]); y1[j] = gelu_tanh(y1[j]); }
;                         s1 += (y0[0] + y0[1]) + (y0[2] + y0[3]) + (y1[0] + y1[1]) + (y1[2] + y1[3]);
;                         s2 += (y0[0] * y0[0] + y0[1] * y0[1]) + (y0[2] * y0[2] + y0[3] * y0[3]) + (y1[0] * y1[0] + y1[1] * y1[1]) + (y1[2] * y1[2] + y1[3] * y1[3]);
;                         u32x4 w; w.x = pk2(y0[0], y0[1]); w.y = pk2(y0[2], y0[3]); w.z = pk2(y1[0], y1[1]); w.w = pk2(y1[2], y1[3]);
;                         *(u32x4*)(dst + (size_t)row * 512 + cb + 32 * bj + 8 * fq) = w;
;                     }
;                     if (isv) {
;                         s1 = sum_fq(s1); s2 = sum_fq(s2);
;                         if (fq == 0) { float* sp = stats + (size_t)row * 16 + ((pn - 5) * 4 + wc) * 2; sp[0] = s1; sp[1] = s2; }
;                     }
;                 }
.LBB0_340:
	v_add_u32_e32 v132, 0x80, v128
	v_ashrrev_i32_e32 v133, 31, v132
	v_lshlrev_b64 v[134:135], 10, v[132:133]
	v_lshl_add_u64 v[154:155], v[130:131], 0, v[134:135]
	v_mul_f32_e32 v134, 0xbdd2d3e7, v56
	v_fmaak_f32 v134, v56, v134, 0xc0135761
	v_mul_f32_e32 v135, 0xbdd2d3e7, v61
	v_mul_f32_e32 v134, v56, v134
	v_fmaak_f32 v135, v61, v135, 0xc0135761
	v_mul_f32_e32 v135, v61, v135
	v_exp_f32_e32 v134, v134
	v_mul_f32_e32 v129, 0xbdd2d3e7, v60
	v_exp_f32_e32 v135, v135
	v_fmaak_f32 v129, v60, v129, 0xc0135761
	v_mul_f32_e32 v129, v60, v129
	v_add_f32_e32 v134, 1.0, v134
	v_exp_f32_e32 v129, v129
	v_rcp_f32_e32 v136, v134
	v_add_f32_e32 v134, 1.0, v135
	v_rcp_f32_e32 v135, v134
	v_mul_f32_e32 v134, 0xbdd2d3e7, v57
	v_fmaak_f32 v134, v57, v134, 0xc0135761
	v_mul_f32_e32 v134, v57, v134
	v_add_f32_e32 v129, 1.0, v129
	v_rcp_f32_e32 v129, v129
	v_exp_f32_e32 v137, v134
	v_mul_f32_e32 v139, 0xbdd2d3e7, v63
	v_mul_f32_e32 v138, 0xbdd2d3e7, v58
	v_mul_f32_e32 v134, v60, v129
	v_mul_f32_e32 v129, v56, v136
	v_add_f32_e32 v136, 1.0, v137
	v_mul_f32_e32 v137, 0xbdd2d3e7, v62
	v_fmaak_f32 v139, v63, v139, 0xc0135761
	v_mul_f32_e32 v140, 0xbdd2d3e7, v59
	v_fmaak_f32 v137, v62, v137, 0xc0135761
	v_fmaak_f32 v138, v58, v138, 0xc0135761
	v_mul_f32_e32 v139, v63, v139
	v_fmaak_f32 v140, v59, v140, 0xc0135761
	v_mul_f32_e32 v137, v62, v137
	v_mul_f32_e32 v138, v58, v138
	v_mul_f32_e32 v140, v59, v140
	v_exp_f32_e32 v139, v139
	v_exp_f32_e32 v137, v137
	v_exp_f32_e32 v138, v138
	v_exp_f32_e32 v140, v140
	v_add_f32_e32 v139, 1.0, v139
	v_add_f32_e32 v137, 1.0, v137
	v_add_f32_e32 v138, 1.0, v138
	v_rcp_f32_e32 v141, v139
	v_add_f32_e32 v139, 1.0, v140
	v_rcp_f32_e32 v136, v136
	v_rcp_f32_e32 v137, v137
	v_rcp_f32_e32 v138, v138
	v_rcp_f32_e32 v140, v139
	v_mul_f32_e32 v135, v61, v135
	v_cvt_pk_bf16_f32 v142, v134, v135
	v_mul_f32_e32 v136, v57, v136
	v_mul_f32_e32 v137, v62, v137
	v_mul_f32_e32 v139, v58, v138
	v_mul_f32_e32 v138, v63, v141
	v_mul_f32_e32 v140, v59, v140
	v_cvt_pk_bf16_f32 v143, v137, v138
	v_cvt_pk_bf16_f32 v144, v129, v136
	v_cvt_pk_bf16_f32 v145, v139, v140
	global_store_dwordx4 v[154:155], v[142:145], off
	v_mul_f32_e32 v141, 0xbdd2d3e7, v52
	v_fmaak_f32 v141, v52, v141, 0xc0135761
	v_mul_f32_e32 v142, 0xbdd2d3e7, v44
	v_fmaak_f32 v142, v44, v142, 0xc0135761
	v_mul_f32_e32 v143, 0xbdd2d3e7, v53
	v_mul_f32_e32 v142, v44, v142
	v_fmaak_f32 v143, v53, v143, 0xc0135761
	v_mul_f32_e32 v143, v53, v143
	v_exp_f32_e32 v142, v142
	v_exp_f32_e32 v143, v143
	v_mul_f32_e32 v141, v52, v141
	v_add_f32_e32 v142, 1.0, v142
	v_exp_f32_e32 v141, v141
	v_rcp_f32_e32 v144, v142
	v_add_f32_e32 v142, 1.0, v143
	v_rcp_f32_e32 v143, v142
	v_mul_f32_e32 v142, 0xbdd2d3e7, v45
	v_fmaak_f32 v142, v45, v142, 0xc0135761
	v_mul_f32_e32 v142, v45, v142
	v_add_f32_e32 v141, 1.0, v141
	v_rcp_f32_e32 v141, v141
	v_exp_f32_e32 v145, v142
	v_mul_f32_e32 v147, 0xbdd2d3e7, v55
	v_mul_f32_e32 v146, 0xbdd2d3e7, v46
	v_mul_f32_e32 v142, v52, v141
	v_mul_f32_e32 v141, v44, v144
	v_add_f32_e32 v144, 1.0, v145
	v_mul_f32_e32 v145, 0xbdd2d3e7, v54
	v_fmaak_f32 v147, v55, v147, 0xc0135761
	v_mul_f32_e32 v148, 0xbdd2d3e7, v47
	v_fmaak_f32 v145, v54, v145, 0xc0135761
	v_fmaak_f32 v146, v46, v146, 0xc0135761
	v_mul_f32_e32 v147, v55, v147
	v_fmaak_f32 v148, v47, v148, 0xc0135761
	v_mul_f32_e32 v145, v54, v145
	v_mul_f32_e32 v146, v46, v146
	v_mul_f32_e32 v148, v47, v148
	v_exp_f32_e32 v147, v147
	v_exp_f32_e32 v145, v145
	v_exp_f32_e32 v146, v146
	v_exp_f32_e32 v148, v148
	v_add_f32_e32 v147, 1.0, v147
	v_add_f32_e32 v145, 1.0, v145
	v_add_f32_e32 v146, 1.0, v146
	v_rcp_f32_e32 v149, v147
	v_add_f32_e32 v147, 1.0, v148
	v_rcp_f32_e32 v144, v144
	v_rcp_f32_e32 v145, v145
	v_rcp_f32_e32 v146, v146
	v_rcp_f32_e32 v148, v147
	v_mul_f32_e32 v143, v53, v143
	v_mul_f32_e32 v144, v45, v144
	v_mul_f32_e32 v145, v54, v145
	v_mul_f32_e32 v147, v46, v146
	v_mul_f32_e32 v146, v55, v149
	v_mul_f32_e32 v148, v47, v148
	s_and_b64 vcc, exec, s[16:17]
	v_cvt_pk_bf16_f32 v150, v142, v143
	v_cvt_pk_bf16_f32 v151, v145, v146
	v_cvt_pk_bf16_f32 v152, v141, v144
	v_cvt_pk_bf16_f32 v153, v147, v148
	global_store_dwordx4 v[154:155], v[150:153], off offset:64
	s_cbranch_vccnz .LBB0_344
	s_nop 0
	v_mul_f32_e32 v150, v135, v135
	v_mul_f32_e32 v151, v138, v138
	v_fmac_f32_e32 v150, v134, v134
	v_fmac_f32_e32 v151, v137, v137
	v_add_f32_e32 v150, v150, v151
	v_mul_f32_e32 v151, v136, v136
	v_fmac_f32_e32 v151, v129, v129
	v_add_f32_e32 v134, v134, v135
	v_add_f32_e32 v135, v137, v138
	v_mul_f32_e32 v149, v140, v140
	v_add_f32_e32 v150, v150, v151
	v_mul_f32_e32 v151, v143, v143
	v_mul_f32_e32 v152, v146, v146
	v_add_f32_e32 v134, v134, v135
	v_add_f32_e32 v129, v129, v136
	v_add_f32_e32 v135, v142, v143
	v_add_f32_e32 v136, v145, v146
	v_fmac_f32_e32 v149, v139, v139
	v_fmac_f32_e32 v151, v142, v142
	v_fmac_f32_e32 v152, v145, v145
	v_add_f32_e32 v139, v139, v140
	v_add_f32_e32 v129, v134, v129
	v_add_f32_e32 v135, v135, v136
	v_add_f32_e32 v136, v141, v144
	v_add_f32_e32 v151, v151, v152
	v_mul_f32_e32 v152, v144, v144
	v_add_f32_e32 v129, v139, v129
	v_add_f32_e32 v134, v147, v148
	v_add_f32_e32 v135, v135, v136
	v_add_f32_e32 v149, v149, v150
	v_mul_f32_e32 v150, v148, v148
	v_fmac_f32_e32 v152, v141, v141
	v_add_f32_e32 v129, 0, v129
	v_add_f32_e32 v134, v134, v135
	v_fmac_f32_e32 v150, v147, v147
	v_add_f32_e32 v151, v151, v152
	v_add_f32_e32 v129, v129, v134
	v_add_f32_e32 v150, v150, v151
	v_mov_b32_e32 v134, v129
	v_add_f32_e32 v149, v149, v150
	s_nop 0
	v_permlane16_swap_b32_e32 v129, v134
	v_add_f32_e32 v134, v129, v134
	v_mov_b32_e32 v129, v149
	s_nop 1
	v_permlane16_swap_b32_e32 v149, v129
	v_add_f32_e32 v135, v149, v129
	v_mov_b32_e32 v136, v134
	v_mov_b32_e32 v137, v135
	s_nop 0
	v_permlane32_swap_b32_e32 v134, v136
	v_permlane32_swap_b32_e32 v135, v137
	s_and_saveexec_b64 s[26:27], s[12:13]
	s_cbranch_execz .LBB0_343
	v_lshlrev_b64 v[132:133], 6, v[132:133]
	v_lshl_add_u64 v[132:133], s[6:7], 0, v[132:133]
	v_pk_add_f32 v[134:135], v[134:135], v[136:137]
	global_store_dwordx2 v[132:133], v[134:135], off

; __device__ __forceinline__ unsigned pk2(float lo, float hi) { return pg8::cvt_pk_bf16(lo, hi); }
; __device__ __forceinline__ float gelu_tanh(float x) {
;     const float u = x * (0.7978845608028654f + 0.035677408136300125f * x * x);
;     return x * __builtin_amdgcn_rcpf(1.0f + __builtin_amdgcn_exp2f(-2.8853900817779268f * u));
;     __device__ __forceinline__ void operator()(const f32x4 (&acc)[2][2][4][2], const pg8::Unit& u, int wr, int wc, int fr, int fq) const {
;     ...
;         } else {
;             const bool isv = pn >= 5;
;             bf16* dst = isv ? VG : U;
;             const int cb = ((pn - (isv ? 5 : 3)) * 4 + wc) * 64;
; #pragma unroll
;             for (int ai = 0; ai < 2; ++ai)
; #pragma unroll
;                 for (int m = 0; m < 4; ++m) {
;                     const int row = pm * 256 + ai * 128 + wr * 64 + m * 16 + fr;
;                     float s1 = 0.f, s2 = 0.f;
; #pragma unroll
;                     for (int bj = 0; bj < 2; ++bj) {
;                         f32x4 y0 = acc[ai][bj][m][0], y1 = acc[ai][bj][m][1];
; #pragma unroll
;                         for (int j = 0; j < 4; ++j) { y0[j] = gelu_tanh(y0[j]); y1[j] = gelu_tanh(y1[j]); }
;                         s1 += (y0[0] + y0[1]) + (y0[2] + y0[3]) + (y1[0] + y1[1]) + (y1[2] + y1[3]);
;                         s2 += (y0[0] * y0[0] + y0[1] * y0[1]) + (y0[2] * y0[2] + y0[3] * y0[3]) + (y1[0] * y1[0] + y1[1] * y1[1]) + (y1[2] * y1[2] + y1[3] * y1[3]);
;                         u32x4 w; w.x = pk2(y0[0], y0[1]); w.y = pk2(y0[2], y0[3]); w.z = pk2(y1[0], y1[1]); w.w = pk2(y1[2], y1[3]);
;                         *(u32x4*)(dst + (size_t)row * 512 + cb + 32 * bj + 8 * fq) = w;
;                     }
;                     if (isv) {
;                         s1 = sum_fq(s1); s2 = sum_fq(s2);
;                         if (fq == 0) { float* sp = stats + (size_t)row * 16 + ((pn - 5) * 4 + wc) * 2; sp[0] = s1; sp[1] = s2; }
;                     }
;                 }
.LBB0_344:
	v_add_u32_e32 v132, 0x90, v128
	v_ashrrev_i32_e32 v133, 31, v132
	v_lshlrev_b64 v[134:135], 10, v[132:133]
	v_lshl_add_u64 v[154:155], v[130:131], 0, v[134:135]
	v_mul_f32_e32 v134, 0xbdd2d3e7, v40
	v_fmaak_f32 v134, v40, v134, 0xc0135761
	v_mul_f32_e32 v135, 0xbdd2d3e7, v49
	v_mul_f32_e32 v134, v40, v134
	v_fmaak_f32 v135, v49, v135, 0xc0135761
	v_mul_f32_e32 v135, v49, v135
	v_exp_f32_e32 v134, v134
	v_mul_f32_e32 v129, 0xbdd2d3e7, v48
	v_exp_f32_e32 v135, v135
	v_fmaak_f32 v129, v48, v129, 0xc0135761
	v_mul_f32_e32 v129, v48, v129
	v_add_f32_e32 v134, 1.0, v134
	v_exp_f32_e32 v129, v129
	v_rcp_f32_e32 v136, v134
	v_add_f32_e32 v134, 1.0, v135
	v_rcp_f32_e32 v135, v134
	v_mul_f32_e32 v134, 0xbdd2d3e7, v41
	v_fmaak_f32 v134, v41, v134, 0xc0135761
	v_mul_f32_e32 v134, v41, v134
	v_add_f32_e32 v129, 1.0, v129
	v_rcp_f32_e32 v129, v129
	v_exp_f32_e32 v137, v134
	v_mul_f32_e32 v139, 0xbdd2d3e7, v51
	v_mul_f32_e32 v138, 0xbdd2d3e7, v42
	v_mul_f32_e32 v134, v48, v129
	v_mul_f32_e32 v129, v40, v136
	v_add_f32_e32 v136, 1.0, v137
	v_mul_f32_e32 v137, 0xbdd2d3e7, v50
	v_fmaak_f32 v139, v51, v139, 0xc0135761
	v_mul_f32_e32 v140, 0xbdd2d3e7, v43
	v_fmaak_f32 v137, v50, v137, 0xc0135761
	v_fmaak_f32 v138, v42, v138, 0xc0135761
	v_mul_f32_e32 v139, v51, v139
	v_fmaak_f32 v140, v43, v140, 0xc0135761
	v_mul_f32_e32 v137, v50, v137
	v_mul_f32_e32 v138, v42, v138
	v_mul_f32_e32 v140, v43, v140
	v_exp_f32_e32 v139, v139
	v_exp_f32_e32 v137, v137
	v_exp_f32_e32 v138, v138
	v_exp_f32_e32 v140, v140
	v_add_f32_e32 v139, 1.0, v139
	v_add_f32_e32 v137, 1.0, v137
	v_add_f32_e32 v138, 1.0, v138
	v_rcp_f32_e32 v141, v139
	v_add_f32_e32 v139, 1.0, v140
	v_rcp_f32_e32 v136, v136
	v_rcp_f32_e32 v137, v137
	v_rcp_f32_e32 v138, v138
	v_rcp_f32_e32 v140, v139
	v_mul_f32_e32 v135, v49, v135
	v_cvt_pk_bf16_f32 v142, v134, v135
	v_mul_f32_e32 v136, v41, v136
	v_mul_f32_e32 v137, v50, v137
	v_mul_f32_e32 v139, v42, v138
	v_mul_f32_e32 v138, v51, v141
	v_mul_f32_e32 v140, v43, v140
	v_cvt_pk_bf16_f32 v143, v137, v138
	v_cvt_pk_bf16_f32 v144, v129, v136
	v_cvt_pk_bf16_f32 v145, v139, v140
	global_store_dwordx4 v[154:155], v[142:145], off
	v_mul_f32_e32 v141, 0xbdd2d3e7, v36
	v_fmaak_f32 v141, v36, v141, 0xc0135761
	v_mul_f32_e32 v142, 0xbdd2d3e7, v28
	v_fmaak_f32 v142, v28, v142, 0xc0135761
	v_mul_f32_e32 v143, 0xbdd2d3e7, v37
	v_mul_f32_e32 v142, v28, v142
	v_fmaak_f32 v143, v37, v143, 0xc0135761
	v_mul_f32_e32 v143, v37, v143
	v_exp_f32_e32 v142, v142
	v_exp_f32_e32 v143, v143
	v_mul_f32_e32 v141, v36, v141
	v_add_f32_e32 v142, 1.0, v142
	v_exp_f32_e32 v141, v141
	v_rcp_f32_e32 v144, v142
	v_add_f32_e32 v142, 1.0, v143
	v_rcp_f32_e32 v143, v142
	v_mul_f32_e32 v142, 0xbdd2d3e7, v29
	v_fmaak_f32 v142, v29, v142, 0xc0135761
	v_mul_f32_e32 v142, v29, v142
	v_add_f32_e32 v141, 1.0, v141
	v_rcp_f32_e32 v141, v141
	v_exp_f32_e32 v145, v142
	v_mul_f32_e32 v147, 0xbdd2d3e7, v39
	v_mul_f32_e32 v146, 0xbdd2d3e7, v30
	v_mul_f32_e32 v142, v36, v141
	v_mul_f32_e32 v141, v28, v144
	v_add_f32_e32 v144, 1.0, v145
	v_mul_f32_e32 v145, 0xbdd2d3e7, v38
	v_fmaak_f32 v147, v39, v147, 0xc0135761
	v_mul_f32_e32 v148, 0xbdd2d3e7, v31
	v_fmaak_f32 v145, v38, v145, 0xc0135761
	v_fmaak_f32 v146, v30, v146, 0xc0135761
	v_mul_f32_e32 v147, v39, v147
	v_fmaak_f32 v148, v31, v148, 0xc0135761
	v_mul_f32_e32 v145, v38, v145
	v_mul_f32_e32 v146, v30, v146
	v_mul_f32_e32 v148, v31, v148
	v_exp_f32_e32 v147, v147
	v_exp_f32_e32 v145, v145
	v_exp_f32_e32 v146, v146
	v_exp_f32_e32 v148, v148
	v_add_f32_e32 v147, 1.0, v147
	v_add_f32_e32 v145, 1.0, v145
	v_add_f32_e32 v146, 1.0, v146
	v_rcp_f32_e32 v149, v147
	v_add_f32_e32 v147, 1.0, v148
	v_rcp_f32_e32 v144, v144
	v_rcp_f32_e32 v145, v145
	v_rcp_f32_e32 v146, v146
	v_rcp_f32_e32 v148, v147
	v_mul_f32_e32 v143, v37, v143
	v_mul_f32_e32 v144, v29, v144
	v_mul_f32_e32 v145, v38, v145
	v_mul_f32_e32 v147, v30, v146
	v_mul_f32_e32 v146, v39, v149
	v_mul_f32_e32 v148, v31, v148
	s_and_b64 vcc, exec, s[16:17]
	v_cvt_pk_bf16_f32 v150, v142, v143
	v_cvt_pk_bf16_f32 v151, v145, v146
	v_cvt_pk_bf16_f32 v152, v141, v144
	v_cvt_pk_bf16_f32 v153, v147, v148
	global_store_dwordx4 v[154:155], v[150:153], off offset:64
	s_cbranch_vccnz .LBB0_348
	s_nop 0
	v_mul_f32_e32 v150, v135, v135
	v_mul_f32_e32 v151, v138, v138
	v_fmac_f32_e32 v150, v134, v134
	v_fmac_f32_e32 v151, v137, v137
	v_add_f32_e32 v150, v150, v151
	v_mul_f32_e32 v151, v136, v136
	v_fmac_f32_e32 v151, v129, v129
	v_add_f32_e32 v134, v134, v135
	v_add_f32_e32 v135, v137, v138
	v_mul_f32_e32 v149, v140, v140
	v_add_f32_e32 v150, v150, v151
	v_mul_f32_e32 v151, v143, v143
	v_mul_f32_e32 v152, v146, v146
	v_add_f32_e32 v134, v134, v135
	v_add_f32_e32 v129, v129, v136
	v_add_f32_e32 v135, v142, v143
	v_add_f32_e32 v136, v145, v146
	v_fmac_f32_e32 v149, v139, v139
	v_fmac_f32_e32 v151, v142, v142
	v_fmac_f32_e32 v152, v145, v145
	v_add_f32_e32 v139, v139, v140
	v_add_f32_e32 v129, v134, v129
	v_add_f32_e32 v135, v135, v136
	v_add_f32_e32 v136, v141, v144
	v_add_f32_e32 v151, v151, v152
	v_mul_f32_e32 v152, v144, v144
	v_add_f32_e32 v129, v139, v129
	v_add_f32_e32 v134, v147, v148
	v_add_f32_e32 v135, v135, v136
	v_add_f32_e32 v149, v149, v150
	v_mul_f32_e32 v150, v148, v148
	v_fmac_f32_e32 v152, v141, v141
	v_add_f32_e32 v129, 0, v129
	v_add_f32_e32 v134, v134, v135
	v_fmac_f32_e32 v150, v147, v147
	v_add_f32_e32 v151, v151, v152
	v_add_f32_e32 v129, v129, v134
	v_add_f32_e32 v150, v150, v151
	v_mov_b32_e32 v134, v129
	v_add_f32_e32 v149, v149, v150
	s_nop 0
	v_permlane16_swap_b32_e32 v129, v134
	v_add_f32_e32 v134, v129, v134
	v_mov_b32_e32 v129, v149
	s_nop 1
	v_permlane16_swap_b32_e32 v149, v129
	v_add_f32_e32 v135, v149, v129
	v_mov_b32_e32 v136, v134
	v_mov_b32_e32 v137, v135
	s_nop 0
	v_permlane32_swap_b32_e32 v134, v136
	v_permlane32_swap_b32_e32 v135, v137
	s_and_saveexec_b64 s[26:27], s[12:13]
	s_cbranch_execz .LBB0_347
	v_lshlrev_b64 v[132:133], 6, v[132:133]
	v_lshl_add_u64 v[132:133], s[6:7], 0, v[132:133]
	v_pk_add_f32 v[134:135], v[134:135], v[136:137]
	global_store_dwordx2 v[132:133], v[134:135], off

; __device__ __forceinline__ unsigned pk2(float lo, float hi) { return pg8::cvt_pk_bf16(lo, hi); }
; __device__ __forceinline__ float gelu_tanh(float x) {
;     const float u = x * (0.7978845608028654f + 0.035677408136300125f * x * x);
;     return x * __builtin_amdgcn_rcpf(1.0f + __builtin_amdgcn_exp2f(-2.8853900817779268f * u));
;     __device__ __forceinline__ void operator()(const f32x4 (&acc)[2][2][4][2], const pg8::Unit& u, int wr, int wc, int fr, int fq) const {
;     ...
;         } else {
;             const bool isv = pn >= 5;
;             bf16* dst = isv ? VG : U;
;             const int cb = ((pn - (isv ? 5 : 3)) * 4 + wc) * 64;
; #pragma unroll
;             for (int ai = 0; ai < 2; ++ai)
; #pragma unroll
;                 for (int m = 0; m < 4; ++m) {
;                     const int row = pm * 256 + ai * 128 + wr * 64 + m * 16 + fr;
;                     float s1 = 0.f, s2 = 0.f;
; #pragma unroll
;                     for (int bj = 0; bj < 2; ++bj) {
;                         f32x4 y0 = acc[ai][bj][m][0], y1 = acc[ai][bj][m][1];
; #pragma unroll
;                         for (int j = 0; j < 4; ++j) { y0[j] = gelu_tanh(y0[j]); y1[j] = gelu_tanh(y1[j]); }
;                         s1 += (y0[0] + y0[1]) + (y0[2] + y0[3]) + (y1[0] + y1[1]) + (y1[2] + y1[3]);
;                         s2 += (y0[0] * y0[0] + y0[1] * y0[1]) + (y0[2] * y0[2] + y0[3] * y0[3]) + (y1[0] * y1[0] + y1[1] * y1[1]) + (y1[2] * y1[2] + y1[3] * y1[3]);
;                         u32x4 w; w.x = pk2(y0[0], y0[1]); w.y = pk2(y0[2], y0[3]); w.z = pk2(y1[0], y1[1]); w.w = pk2(y1[2], y1[3]);
;                         *(u32x4*)(dst + (size_t)row * 512 + cb + 32 * bj + 8 * fq) = w;
;                     }
;                     if (isv) {
;                         s1 = sum_fq(s1); s2 = sum_fq(s2);
;                         if (fq == 0) { float* sp = stats + (size_t)row * 16 + ((pn - 5) * 4 + wc) * 2; sp[0] = s1; sp[1] = s2; }
;                     }
;                 }
.LBB0_348:
	v_add_u32_e32 v132, 0xa0, v128
	v_ashrrev_i32_e32 v133, 31, v132
	v_lshlrev_b64 v[134:135], 10, v[132:133]
	v_lshl_add_u64 v[154:155], v[130:131], 0, v[134:135]
	v_mul_f32_e32 v134, 0xbdd2d3e7, v24
	v_fmaak_f32 v134, v24, v134, 0xc0135761
	v_mul_f32_e32 v135, 0xbdd2d3e7, v33
	v_mul_f32_e32 v134, v24, v134
	v_fmaak_f32 v135, v33, v135, 0xc0135761
	v_mul_f32_e32 v135, v33, v135
	v_exp_f32_e32 v134, v134
	v_mul_f32_e32 v129, 0xbdd2d3e7, v32
	v_exp_f32_e32 v135, v135
	v_fmaak_f32 v129, v32, v129, 0xc0135761
	v_mul_f32_e32 v129, v32, v129
	v_add_f32_e32 v134, 1.0, v134
	v_exp_f32_e32 v129, v129
	v_rcp_f32_e32 v136, v134
	v_add_f32_e32 v134, 1.0, v135
	v_rcp_f32_e32 v135, v134
	v_mul_f32_e32 v134, 0xbdd2d3e7, v25
	v_fmaak_f32 v134, v25, v134, 0xc0135761
	v_mul_f32_e32 v134, v25, v134
	v_add_f32_e32 v129, 1.0, v129
	v_rcp_f32_e32 v129, v129
	v_exp_f32_e32 v137, v134
	v_mul_f32_e32 v139, 0xbdd2d3e7, v35
	v_mul_f32_e32 v138, 0xbdd2d3e7, v26
	v_mul_f32_e32 v134, v32, v129
	v_mul_f32_e32 v129, v24, v136
	v_add_f32_e32 v136, 1.0, v137
	v_mul_f32_e32 v137, 0xbdd2d3e7, v34
	v_fmaak_f32 v139, v35, v139, 0xc0135761
	v_mul_f32_e32 v140, 0xbdd2d3e7, v27
	v_fmaak_f32 v137, v34, v137, 0xc0135761
	v_fmaak_f32 v138, v26, v138, 0xc0135761
	v_mul_f32_e32 v139, v35, v139
	v_fmaak_f32 v140, v27, v140, 0xc0135761
	v_mul_f32_e32 v137, v34, v137
	v_mul_f32_e32 v138, v26, v138
	v_mul_f32_e32 v140, v27, v140
	v_exp_f32_e32 v139, v139
	v_exp_f32_e32 v137, v137
	v_exp_f32_e32 v138, v138
	v_exp_f32_e32 v140, v140
	v_add_f32_e32 v139, 1.0, v139
	v_add_f32_e32 v137, 1.0, v137
	v_add_f32_e32 v138, 1.0, v138
	v_rcp_f32_e32 v141, v139
	v_add_f32_e32 v139, 1.0, v140
	v_rcp_f32_e32 v136, v136
	v_rcp_f32_e32 v137, v137
	v_rcp_f32_e32 v138, v138
	v_rcp_f32_e32 v140, v139
	v_mul_f32_e32 v135, v33, v135
	v_cvt_pk_bf16_f32 v142, v134, v135
	v_mul_f32_e32 v136, v25, v136
	v_mul_f32_e32 v137, v34, v137
	v_mul_f32_e32 v139, v26, v138
	v_mul_f32_e32 v138, v35, v141
	v_mul_f32_e32 v140, v27, v140
	v_cvt_pk_bf16_f32 v143, v137, v138
	v_cvt_pk_bf16_f32 v144, v129, v136
	v_cvt_pk_bf16_f32 v145, v139, v140
	global_store_dwordx4 v[154:155], v[142:145], off
	v_mul_f32_e32 v141, 0xbdd2d3e7, v20
	v_fmaak_f32 v141, v20, v141, 0xc0135761
	v_mul_f32_e32 v142, 0xbdd2d3e7, v12
	v_fmaak_f32 v142, v12, v142, 0xc0135761
	v_mul_f32_e32 v143, 0xbdd2d3e7, v21
	v_mul_f32_e32 v142, v12, v142
	v_fmaak_f32 v143, v21, v143, 0xc0135761
	v_mul_f32_e32 v143, v21, v143
	v_exp_f32_e32 v142, v142
	v_exp_f32_e32 v143, v143
	v_mul_f32_e32 v141, v20, v141
	v_add_f32_e32 v142, 1.0, v142
	v_exp_f32_e32 v141, v141
	v_rcp_f32_e32 v144, v142
	v_add_f32_e32 v142, 1.0, v143
	v_rcp_f32_e32 v143, v142
	v_mul_f32_e32 v142, 0xbdd2d3e7, v13
	v_fmaak_f32 v142, v13, v142, 0xc0135761
	v_mul_f32_e32 v142, v13, v142
	v_add_f32_e32 v141, 1.0, v141
	v_rcp_f32_e32 v141, v141
	v_exp_f32_e32 v145, v142
	v_mul_f32_e32 v147, 0xbdd2d3e7, v23
	v_mul_f32_e32 v146, 0xbdd2d3e7, v14
	v_mul_f32_e32 v142, v20, v141
	v_mul_f32_e32 v141, v12, v144
	v_add_f32_e32 v144, 1.0, v145
	v_mul_f32_e32 v145, 0xbdd2d3e7, v22
	v_fmaak_f32 v147, v23, v147, 0xc0135761
	v_mul_f32_e32 v148, 0xbdd2d3e7, v15
	v_fmaak_f32 v145, v22, v145, 0xc0135761
	v_fmaak_f32 v146, v14, v146, 0xc0135761
	v_mul_f32_e32 v147, v23, v147
	v_fmaak_f32 v148, v15, v148, 0xc0135761
	v_mul_f32_e32 v145, v22, v145
	v_mul_f32_e32 v146, v14, v146
	v_mul_f32_e32 v148, v15, v148
	v_exp_f32_e32 v147, v147
	v_exp_f32_e32 v145, v145
	v_exp_f32_e32 v146, v146
	v_exp_f32_e32 v148, v148
	v_add_f32_e32 v147, 1.0, v147
	v_add_f32_e32 v145, 1.0, v145
	v_add_f32_e32 v146, 1.0, v146
	v_rcp_f32_e32 v149, v147
	v_add_f32_e32 v147, 1.0, v148
	v_rcp_f32_e32 v144, v144
	v_rcp_f32_e32 v145, v145
	v_rcp_f32_e32 v146, v146
	v_rcp_f32_e32 v148, v147
	v_mul_f32_e32 v143, v21, v143
	v_mul_f32_e32 v144, v13, v144
	v_mul_f32_e32 v145, v22, v145
	v_mul_f32_e32 v147, v14, v146
	v_mul_f32_e32 v146, v23, v149
	v_mul_f32_e32 v148, v15, v148
	s_and_b64 vcc, exec, s[16:17]
	v_cvt_pk_bf16_f32 v150, v142, v143
	v_cvt_pk_bf16_f32 v151, v145, v146
	v_cvt_pk_bf16_f32 v152, v141, v144
	v_cvt_pk_bf16_f32 v153, v147, v148
	global_store_dwordx4 v[154:155], v[150:153], off offset:64
	s_cbranch_vccnz .LBB0_352
	s_nop 0
	v_mul_f32_e32 v150, v135, v135
	v_mul_f32_e32 v151, v138, v138
	v_fmac_f32_e32 v150, v134, v134
	v_fmac_f32_e32 v151, v137, v137
	v_add_f32_e32 v150, v150, v151
	v_mul_f32_e32 v151, v136, v136
	v_fmac_f32_e32 v151, v129, v129
	v_add_f32_e32 v134, v134, v135
	v_add_f32_e32 v135, v137, v138
	v_mul_f32_e32 v149, v140, v140
	v_add_f32_e32 v150, v150, v151
	v_mul_f32_e32 v151, v143, v143
	v_mul_f32_e32 v152, v146, v146
	v_add_f32_e32 v134, v134, v135
	v_add_f32_e32 v129, v129, v136
	v_add_f32_e32 v135, v142, v143
	v_add_f32_e32 v136, v145, v146
	v_fmac_f32_e32 v149, v139, v139
	v_fmac_f32_e32 v151, v142, v142
	v_fmac_f32_e32 v152, v145, v145
	v_add_f32_e32 v139, v139, v140
	v_add_f32_e32 v129, v134, v129
	v_add_f32_e32 v135, v135, v136
	v_add_f32_e32 v136, v141, v144
	v_add_f32_e32 v151, v151, v152
	v_mul_f32_e32 v152, v144, v144
	v_add_f32_e32 v129, v139, v129
	v_add_f32_e32 v134, v147, v148
	v_add_f32_e32 v135, v135, v136
	v_add_f32_e32 v149, v149, v150
	v_mul_f32_e32 v150, v148, v148
	v_fmac_f32_e32 v152, v141, v141
	v_add_f32_e32 v129, 0, v129
	v_add_f32_e32 v134, v134, v135
	v_fmac_f32_e32 v150, v147, v147
	v_add_f32_e32 v151, v151, v152
	v_add_f32_e32 v129, v129, v134
	v_add_f32_e32 v150, v150, v151
	v_mov_b32_e32 v134, v129
	v_add_f32_e32 v149, v149, v150
	s_nop 0
	v_permlane16_swap_b32_e32 v129, v134
	v_add_f32_e32 v134, v129, v134
	v_mov_b32_e32 v129, v149
	s_nop 1
	v_permlane16_swap_b32_e32 v149, v129
	v_add_f32_e32 v135, v149, v129
	v_mov_b32_e32 v136, v134
	v_mov_b32_e32 v137, v135
	s_nop 0
	v_permlane32_swap_b32_e32 v134, v136
	v_permlane32_swap_b32_e32 v135, v137
	s_and_saveexec_b64 s[26:27], s[12:13]
	s_cbranch_execz .LBB0_351
	v_lshlrev_b64 v[132:133], 6, v[132:133]
	v_lshl_add_u64 v[132:133], s[6:7], 0, v[132:133]
	v_pk_add_f32 v[134:135], v[134:135], v[136:137]
	global_store_dwordx2 v[132:133], v[134:135], off

; __device__ __forceinline__ unsigned pk2(float lo, float hi) { return pg8::cvt_pk_bf16(lo, hi); }
; __device__ __forceinline__ float gelu_tanh(float x) {
;     const float u = x * (0.7978845608028654f + 0.035677408136300125f * x * x);
;     return x * __builtin_amdgcn_rcpf(1.0f + __builtin_amdgcn_exp2f(-2.8853900817779268f * u));
;     __device__ __forceinline__ void operator()(const f32x4 (&acc)[2][2][4][2], const pg8::Unit& u, int wr, int wc, int fr, int fq) const {
;     ...
;         } else {
;             const bool isv = pn >= 5;
;             bf16* dst = isv ? VG : U;
;             const int cb = ((pn - (isv ? 5 : 3)) * 4 + wc) * 64;
; #pragma unroll
;             for (int ai = 0; ai < 2; ++ai)
; #pragma unroll
;                 for (int m = 0; m < 4; ++m) {
;                     const int row = pm * 256 + ai * 128 + wr * 64 + m * 16 + fr;
;                     float s1 = 0.f, s2 = 0.f;
; #pragma unroll
;                     for (int bj = 0; bj < 2; ++bj) {
;                         f32x4 y0 = acc[ai][bj][m][0], y1 = acc[ai][bj][m][1];
; #pragma unroll
;                         for (int j = 0; j < 4; ++j) { y0[j] = gelu_tanh(y0[j]); y1[j] = gelu_tanh(y1[j]); }
;                         s1 += (y0[0] + y0[1]) + (y0[2] + y0[3]) + (y1[0] + y1[1]) + (y1[2] + y1[3]);
;                         s2 += (y0[0] * y0[0] + y0[1] * y0[1]) + (y0[2] * y0[2] + y0[3] * y0[3]) + (y1[0] * y1[0] + y1[1] * y1[1]) + (y1[2] * y1[2] + y1[3] * y1[3]);
;                         u32x4 w; w.x = pk2(y0[0], y0[1]); w.y = pk2(y0[2], y0[3]); w.z = pk2(y1[0], y1[1]); w.w = pk2(y1[2], y1[3]);
;                         *(u32x4*)(dst + (size_t)row * 512 + cb + 32 * bj + 8 * fq) = w;
;                     }
;                     if (isv) {
;                         s1 = sum_fq(s1); s2 = sum_fq(s2);
;                         if (fq == 0) { float* sp = stats + (size_t)row * 16 + ((pn - 5) * 4 + wc) * 2; sp[0] = s1; sp[1] = s2; }
;                     }
;                 }
.LBB0_352:
	v_add_u32_e32 v132, 0xb0, v128
	v_ashrrev_i32_e32 v133, 31, v132
	v_lshlrev_b64 v[134:135], 10, v[132:133]
	v_lshl_add_u64 v[152:153], v[130:131], 0, v[134:135]
	v_mul_f32_e32 v130, 0xbdd2d3e7, v8
	v_fmaak_f32 v130, v8, v130, 0xc0135761
	v_mul_f32_e32 v131, 0xbdd2d3e7, v17
	v_mul_f32_e32 v130, v8, v130
	v_fmaak_f32 v131, v17, v131, 0xc0135761
	v_mul_f32_e32 v131, v17, v131
	v_exp_f32_e32 v130, v130
	v_mul_f32_e32 v129, 0xbdd2d3e7, v16
	v_exp_f32_e32 v131, v131
	v_fmaak_f32 v129, v16, v129, 0xc0135761
	v_mul_f32_e32 v129, v16, v129
	v_add_f32_e32 v130, 1.0, v130
	v_exp_f32_e32 v129, v129
	v_rcp_f32_e32 v134, v130
	v_add_f32_e32 v130, 1.0, v131
	v_rcp_f32_e32 v131, v130
	v_mul_f32_e32 v130, 0xbdd2d3e7, v9
	v_fmaak_f32 v130, v9, v130, 0xc0135761
	v_mul_f32_e32 v130, v9, v130
	v_add_f32_e32 v129, 1.0, v129
	v_rcp_f32_e32 v129, v129
	v_exp_f32_e32 v135, v130
	v_mul_f32_e32 v137, 0xbdd2d3e7, v19
	v_mul_f32_e32 v136, 0xbdd2d3e7, v10
	v_mul_f32_e32 v130, v16, v129
	v_mul_f32_e32 v129, v8, v134
	v_add_f32_e32 v134, 1.0, v135
	v_mul_f32_e32 v135, 0xbdd2d3e7, v18
	v_fmaak_f32 v137, v19, v137, 0xc0135761
	v_mul_f32_e32 v138, 0xbdd2d3e7, v11
	v_fmaak_f32 v135, v18, v135, 0xc0135761
	v_fmaak_f32 v136, v10, v136, 0xc0135761
	v_mul_f32_e32 v137, v19, v137
	v_fmaak_f32 v138, v11, v138, 0xc0135761
	v_mul_f32_e32 v135, v18, v135
	v_mul_f32_e32 v136, v10, v136
	v_mul_f32_e32 v138, v11, v138
	v_exp_f32_e32 v137, v137
	v_exp_f32_e32 v135, v135
	v_exp_f32_e32 v136, v136
	v_exp_f32_e32 v138, v138
	v_add_f32_e32 v137, 1.0, v137
	v_add_f32_e32 v135, 1.0, v135
	v_add_f32_e32 v136, 1.0, v136
	v_rcp_f32_e32 v139, v137
	v_add_f32_e32 v137, 1.0, v138
	v_rcp_f32_e32 v134, v134
	v_rcp_f32_e32 v135, v135
	v_rcp_f32_e32 v136, v136
	v_rcp_f32_e32 v138, v137
	v_mul_f32_e32 v131, v17, v131
	v_cvt_pk_bf16_f32 v140, v130, v131
	v_mul_f32_e32 v134, v9, v134
	v_mul_f32_e32 v135, v18, v135
	v_mul_f32_e32 v137, v10, v136
	v_mul_f32_e32 v136, v19, v139
	v_mul_f32_e32 v138, v11, v138
	v_cvt_pk_bf16_f32 v141, v135, v136
	v_cvt_pk_bf16_f32 v142, v129, v134
	v_cvt_pk_bf16_f32 v143, v137, v138
	global_store_dwordx4 v[152:153], v[140:143], off
	v_mul_f32_e32 v139, 0xbdd2d3e7, v4
	v_fmaak_f32 v139, v4, v139, 0xc0135761
	v_mul_f32_e32 v140, 0xbdd2d3e7, v0
	v_fmaak_f32 v140, v0, v140, 0xc0135761
	v_mul_f32_e32 v141, 0xbdd2d3e7, v5
	v_mul_f32_e32 v140, v0, v140
	v_fmaak_f32 v141, v5, v141, 0xc0135761
	v_mul_f32_e32 v141, v5, v141
	v_exp_f32_e32 v140, v140
	v_exp_f32_e32 v141, v141
	v_mul_f32_e32 v139, v4, v139
	v_add_f32_e32 v140, 1.0, v140
	v_exp_f32_e32 v139, v139
	v_rcp_f32_e32 v142, v140
	v_add_f32_e32 v140, 1.0, v141
	v_rcp_f32_e32 v141, v140
	v_mul_f32_e32 v140, 0xbdd2d3e7, v1
	v_fmaak_f32 v140, v1, v140, 0xc0135761
	v_mul_f32_e32 v140, v1, v140
	v_add_f32_e32 v139, 1.0, v139
	v_rcp_f32_e32 v139, v139
	v_exp_f32_e32 v143, v140
	v_mul_f32_e32 v145, 0xbdd2d3e7, v7
	v_mul_f32_e32 v144, 0xbdd2d3e7, v2
	v_mul_f32_e32 v140, v4, v139
	v_mul_f32_e32 v139, v0, v142
	v_add_f32_e32 v142, 1.0, v143
	v_mul_f32_e32 v143, 0xbdd2d3e7, v6
	v_fmaak_f32 v145, v7, v145, 0xc0135761
	v_mul_f32_e32 v146, 0xbdd2d3e7, v3
	v_fmaak_f32 v143, v6, v143, 0xc0135761
	v_fmaak_f32 v144, v2, v144, 0xc0135761
	v_mul_f32_e32 v145, v7, v145
	v_fmaak_f32 v146, v3, v146, 0xc0135761
	v_mul_f32_e32 v143, v6, v143
	v_mul_f32_e32 v144, v2, v144
	v_mul_f32_e32 v146, v3, v146
	v_exp_f32_e32 v145, v145
	v_exp_f32_e32 v143, v143
	v_exp_f32_e32 v144, v144
	v_exp_f32_e32 v146, v146
	v_add_f32_e32 v145, 1.0, v145
	v_add_f32_e32 v143, 1.0, v143
	v_add_f32_e32 v144, 1.0, v144
	v_rcp_f32_e32 v147, v145
	v_add_f32_e32 v145, 1.0, v146
	v_rcp_f32_e32 v142, v142
	v_rcp_f32_e32 v143, v143
	v_rcp_f32_e32 v144, v144
	v_rcp_f32_e32 v146, v145
	v_mul_f32_e32 v141, v5, v141
	v_mul_f32_e32 v142, v1, v142
	v_mul_f32_e32 v143, v6, v143
	v_mul_f32_e32 v145, v2, v144
	v_mul_f32_e32 v144, v7, v147
	v_mul_f32_e32 v146, v3, v146
	s_and_b64 vcc, exec, s[16:17]
	v_cvt_pk_bf16_f32 v148, v140, v141
	v_cvt_pk_bf16_f32 v149, v143, v144
	v_cvt_pk_bf16_f32 v150, v139, v142
	v_cvt_pk_bf16_f32 v151, v145, v146
	global_store_dwordx4 v[152:153], v[148:151], off offset:64
	s_cbranch_vccnz .LBB0_356
	s_nop 0
	v_mul_f32_e32 v148, v131, v131
	v_mul_f32_e32 v149, v136, v136
	v_fmac_f32_e32 v148, v130, v130
	v_fmac_f32_e32 v149, v135, v135
	v_add_f32_e32 v148, v148, v149
	v_mul_f32_e32 v149, v134, v134
	v_fmac_f32_e32 v149, v129, v129
	v_add_f32_e32 v130, v130, v131
	v_add_f32_e32 v131, v135, v136
	v_mul_f32_e32 v147, v138, v138
	v_add_f32_e32 v148, v148, v149
	v_mul_f32_e32 v149, v141, v141
	v_mul_f32_e32 v150, v144, v144
	v_add_f32_e32 v130, v130, v131
	v_add_f32_e32 v129, v129, v134
	v_add_f32_e32 v131, v140, v141
	v_add_f32_e32 v134, v143, v144
	v_fmac_f32_e32 v147, v137, v137
	v_fmac_f32_e32 v149, v140, v140
	v_fmac_f32_e32 v150, v143, v143
	v_add_f32_e32 v137, v137, v138
	v_add_f32_e32 v129, v130, v129
	v_add_f32_e32 v131, v131, v134
	v_add_f32_e32 v134, v139, v142
	v_add_f32_e32 v149, v149, v150
	v_mul_f32_e32 v150, v142, v142
	v_add_f32_e32 v129, v137, v129
	v_add_f32_e32 v130, v145, v146
	v_add_f32_e32 v131, v131, v134
	v_add_f32_e32 v147, v147, v148
	v_mul_f32_e32 v148, v146, v146
	v_fmac_f32_e32 v150, v139, v139
	v_add_f32_e32 v129, 0, v129
	v_add_f32_e32 v130, v130, v131
	v_fmac_f32_e32 v148, v145, v145
	v_add_f32_e32 v149, v149, v150
	v_add_f32_e32 v129, v129, v130
	v_add_f32_e32 v148, v148, v149
	v_mov_b32_e32 v130, v129
	v_add_f32_e32 v147, v147, v148
	s_nop 0
	v_permlane16_swap_b32_e32 v129, v130
	v_add_f32_e32 v130, v129, v130
	v_mov_b32_e32 v129, v147
	s_nop 1
	v_permlane16_swap_b32_e32 v147, v129
	v_add_f32_e32 v131, v147, v129
	v_mov_b32_e32 v134, v130
	v_mov_b32_e32 v135, v131
	s_nop 0
	v_permlane32_swap_b32_e32 v130, v134
	v_permlane32_swap_b32_e32 v131, v135
	s_and_saveexec_b64 s[16:17], s[12:13]
	s_cbranch_execz .LBB0_355
	v_lshlrev_b64 v[132:133], 6, v[132:133]
	v_lshl_add_u64 v[132:133], s[6:7], 0, v[132:133]
	v_pk_add_f32 v[130:131], v[130:131], v[134:135]
	global_store_dwordx2 v[132:133], v[130:131], off
